# batched hand-written copy of the surviving cache-window rows (4 loads per thread issued together instead of 2 serialized round trips per iteration)
# baseline (speedup 1.0000x reference)
.LBB0_905:
	s_or_b64 exec, exec, s[4:5]
	s_load_dwordx4 s[4:7], s[78:79], 0x18
	s_load_dwordx2 s[8:9], s[78:79], 0x98
	v_lshlrev_b32_e32 v3, 4, v73
	s_waitcnt lgkmcnt(0)
	s_add_u32 s1, s76, 0
	s_mov_b32 s32, 0x4b70000
	s_mov_b32 vcc_lo, 0x4f70000
	s_cmp_ge_u32 s1, 0x1e0
	s_cselect_b32 s2, 0x1e0, 0
	s_cselect_b64 s[10:11], s[6:7], s[4:5]
	s_cselect_b32 s32, vcc_lo, s32
	s_sub_u32 s1, s1, s2
	s_mul_i32 s2, s1, 0x8889
	s_lshr_b32 s2, s2, 19
	s_mul_i32 vcc_lo, s2, 15
	s_sub_u32 s1, s1, vcc_lo
	s_lshl_b32 s2, s2, 17
	s_lshl_b32 s1, s1, 13
	s_add_u32 s2, s2, s1
	s_add_u32 s98, s2, s32
	s_add_u32 s2, s2, 0x2000
	s_add_u32 s10, s10, s2
	s_addc_u32 s11, s11, 0
	global_load_dwordx4 v[4:7], v3, s[10:11]
	s_add_u32 s1, s76, 256
	s_mov_b32 s32, 0x4b70000
	s_mov_b32 vcc_lo, 0x4f70000
	s_cmp_ge_u32 s1, 0x1e0
	s_cselect_b32 s2, 0x1e0, 0
	s_cselect_b64 s[10:11], s[6:7], s[4:5]
	s_cselect_b32 s32, vcc_lo, s32
	s_sub_u32 s1, s1, s2
	s_mul_i32 s2, s1, 0x8889
	s_lshr_b32 s2, s2, 19
	s_mul_i32 vcc_lo, s2, 15
	s_sub_u32 s1, s1, vcc_lo
	s_lshl_b32 s2, s2, 17
	s_lshl_b32 s1, s1, 13
	s_add_u32 s2, s2, s1
	s_add_u32 s99, s2, s32
	s_add_u32 s2, s2, 0x2000
	s_add_u32 s10, s10, s2
	s_addc_u32 s11, s11, 0
	global_load_dwordx4 v[8:11], v3, s[10:11]
	s_add_u32 s1, s76, 512
	s_mov_b32 s32, 0x4b70000
	s_mov_b32 vcc_lo, 0x4f70000
	s_cmp_ge_u32 s1, 0x1e0
	s_cselect_b32 s2, 0x1e0, 0
	s_cselect_b64 s[10:11], s[6:7], s[4:5]
	s_cselect_b32 s32, vcc_lo, s32
	s_sub_u32 s1, s1, s2
	s_mul_i32 s2, s1, 0x8889
	s_lshr_b32 s2, s2, 19
	s_mul_i32 vcc_lo, s2, 15
	s_sub_u32 s1, s1, vcc_lo
	s_lshl_b32 s2, s2, 17
	s_lshl_b32 s1, s1, 13
	s_add_u32 s2, s2, s1
	s_add_u32 s100, s2, s32
	s_add_u32 s2, s2, 0x2000
	s_add_u32 s10, s10, s2
	s_addc_u32 s11, s11, 0
	global_load_dwordx4 v[12:15], v3, s[10:11]
	s_cmp_lt_u32 s76, 0xc0
	s_cbranch_scc0 .Lcw_ld_done
	s_add_u32 s1, s76, 768
	s_mov_b32 s32, 0x4b70000
	s_mov_b32 vcc_lo, 0x4f70000
	s_cmp_ge_u32 s1, 0x1e0
	s_cselect_b32 s2, 0x1e0, 0
	s_cselect_b64 s[10:11], s[6:7], s[4:5]
	s_cselect_b32 s32, vcc_lo, s32
	s_sub_u32 s1, s1, s2
	s_mul_i32 s2, s1, 0x8889
	s_lshr_b32 s2, s2, 19
	s_mul_i32 vcc_lo, s2, 15
	s_sub_u32 s1, s1, vcc_lo
	s_lshl_b32 s2, s2, 17
	s_lshl_b32 s1, s1, 13
	s_add_u32 s2, s2, s1
	s_add_u32 s101, s2, s32
	s_add_u32 s2, s2, 0x2000
	s_add_u32 s10, s10, s2
	s_addc_u32 s11, s11, 0
	global_load_dwordx4 v[16:19], v3, s[10:11]
.Lcw_ld_done:
	s_waitcnt vmcnt(0)
	s_add_u32 s10, s8, s98
	s_addc_u32 s11, s9, 0
	global_store_dwordx4 v3, v[4:7], s[10:11]
	s_add_u32 s10, s8, s99
	s_addc_u32 s11, s9, 0
	global_store_dwordx4 v3, v[8:11], s[10:11]
	s_add_u32 s10, s8, s100
	s_addc_u32 s11, s9, 0
	global_store_dwordx4 v3, v[12:15], s[10:11]
	s_cmp_lt_u32 s76, 0xc0
	s_cbranch_scc0 .Lcw_done
	s_add_u32 s10, s8, s101
	s_addc_u32 s11, s9, 0
	global_store_dwordx4 v3, v[16:19], s[10:11]
.Lcw_done:
.LBB0_908:
	s_or_b64 exec, exec, s[4:5]
	s_waitcnt lgkmcnt(0)
	s_mov_b64 s[22:23], s[78:79]
	v_mov_b32_e32 v0, v170
	s_barrier
	s_load_dwordx2 s[4:5], s[78:79], 0xa0
	s_load_dwordx2 s[6:7], s[78:79], 0x28
	s_load_dwordx2 s[8:9], s[78:79], 0x98
	s_load_dwordx2 s[10:11], s[78:79], 0x10
	s_load_dwordx4 s[12:15], s[78:79], 0x0
	v_and_b32_e32 v28, 63, v170
	v_lshrrev_b32_e32 v29, 6, v170
	v_lshlrev_b32_e32 v21, 4, v170
	v_lshlrev_b32_e32 v20, 2, v28
	v_readfirstlane_b32 s2, v29
	v_and_b32_e32 v22, 0x7f, v170
	v_lshlrev_b32_e32 v22, 3, v22
	v_lshlrev_b32_e32 v23, 4, v28
	s_lshr_b32 s0, s2, 1
	s_lshl_b32 s1, 2, s0
	s_mul_i32 s41, s0, 0x948000
	v_add_u32_e32 v22, s41, v22
	s_add_u32 s40, s0, 1
	s_lshl_b32 s40, s40, 23
	s_sub_u32 s40, 0x3f800000, s40
	v_mov_b32_e32 v27, s40
	s_lshr_b32 s44, s76, 6
	s_and_b32 s45, s76, 63
	s_cmp_eq_u32 s45, 0
	s_cselect_b32 s38, 1, 0
	s_cmp_eq_u32 s45, 63
	s_cselect_b32 s39, 1, 0
	s_lshl_b32 s45, s45, 5
	s_lshl_b32 s50, s44, 11
	s_add_u32 s50, s50, s45
	s_sub_i32 s52, s50, 15
	s_sub_u32 s53, 16, s1
	s_sub_u32 s37, s1, 1
	s_cmp_eq_u32 s38, 1
	s_cselect_b32 s36, 15, s53
	s_cselect_b32 s37, s37, 0
	s_cselect_b32 s62, 15, 0
	s_waitcnt lgkmcnt(0)
	s_mov_b64 s[16:17], s[12:13]
	s_add_u32 s18, s4, 0x1d900000
	s_addc_u32 s19, s5, 0
	global_load_dwordx4 v[2:5], v21, s[6:7]
	s_add_u32 s41, s2, 0
	s_max_u32 s41, s41, s62
	s_min_u32 s41, s41, 46
	s_lshl_b32 s24, s41, 2
	s_add_i32 s41, s41, s52
	s_lshl_b32 s12, s41, 13
	s_lshr_b32 s13, s41, 19
	s_add_u32 s20, s16, s12
	s_addc_u32 s21, s17, s13
	s_add_u32 s48, s20, 0x1000
	s_addc_u32 s49, s21, 0
	global_load_dwordx4 v[34:37], v23, s[20:21] offset:0
	global_load_dwordx4 v[38:41], v23, s[20:21] offset:1024
	global_load_dwordx4 v[42:45], v23, s[20:21] offset:2048
	global_load_dwordx4 v[46:49], v23, s[20:21] offset:3072
	global_load_dwordx4 v[50:53], v23, s[48:49] offset:0
	global_load_dwordx4 v[54:57], v23, s[48:49] offset:1024
	global_load_dwordx4 v[58:61], v23, s[48:49] offset:2048
	global_load_dwordx4 v[62:65], v23, s[48:49] offset:3072
	s_add_u32 s41, s2, 8
	s_max_u32 s41, s41, s62
	s_min_u32 s41, s41, 46
	s_lshl_b32 s25, s41, 2
	s_add_i32 s41, s41, s52
	s_lshl_b32 s12, s41, 13
	s_lshr_b32 s13, s41, 19
	s_add_u32 s20, s16, s12
	s_addc_u32 s21, s17, s13
	s_add_u32 s48, s20, 0x1000
	s_addc_u32 s49, s21, 0
	global_load_dwordx4 v[66:69], v23, s[20:21] offset:0
	global_load_dwordx4 v[70:73], v23, s[20:21] offset:1024
	global_load_dwordx4 v[74:77], v23, s[20:21] offset:2048
	global_load_dwordx4 v[78:81], v23, s[20:21] offset:3072
	global_load_dwordx4 v[82:85], v23, s[48:49] offset:0
	global_load_dwordx4 v[86:89], v23, s[48:49] offset:1024
	global_load_dwordx4 v[90:93], v23, s[48:49] offset:2048
	global_load_dwordx4 v[94:97], v23, s[48:49] offset:3072
	s_add_u32 s41, s2, 16
	s_max_u32 s41, s41, s62
	s_min_u32 s41, s41, 46
	s_lshl_b32 s26, s41, 2
	s_add_i32 s41, s41, s52
	s_lshl_b32 s12, s41, 13
	s_lshr_b32 s13, s41, 19
	s_add_u32 s20, s16, s12
	s_addc_u32 s21, s17, s13
	s_add_u32 s48, s20, 0x1000
	s_addc_u32 s49, s21, 0
	global_load_dwordx4 v[98:101], v23, s[20:21] offset:0
	global_load_dwordx4 v[102:105], v23, s[20:21] offset:1024
	global_load_dwordx4 v[106:109], v23, s[20:21] offset:2048
	global_load_dwordx4 v[110:113], v23, s[20:21] offset:3072
	global_load_dwordx4 v[114:117], v23, s[48:49] offset:0
	global_load_dwordx4 v[118:121], v23, s[48:49] offset:1024
	global_load_dwordx4 v[122:125], v23, s[48:49] offset:2048
	global_load_dwordx4 v[126:129], v23, s[48:49] offset:3072
	s_waitcnt vmcnt(0)
	v_mul_f32_e32 v130, v34, v34
	v_fmac_f32_e32 v130, v35, v35
	v_fmac_f32_e32 v130, v36, v36
	v_fmac_f32_e32 v130, v37, v37
	v_fmac_f32_e32 v130, v38, v38
	v_fmac_f32_e32 v130, v39, v39
	v_fmac_f32_e32 v130, v40, v40
	v_fmac_f32_e32 v130, v41, v41
	v_fmac_f32_e32 v130, v42, v42
	v_fmac_f32_e32 v130, v43, v43
	v_fmac_f32_e32 v130, v44, v44
	v_fmac_f32_e32 v130, v45, v45
	v_fmac_f32_e32 v130, v46, v46
	v_fmac_f32_e32 v130, v47, v47
	v_fmac_f32_e32 v130, v48, v48
	v_fmac_f32_e32 v130, v49, v49
	v_fmac_f32_e32 v130, v50, v50
	v_fmac_f32_e32 v130, v51, v51
	v_fmac_f32_e32 v130, v52, v52
	v_fmac_f32_e32 v130, v53, v53
	v_fmac_f32_e32 v130, v54, v54
	v_fmac_f32_e32 v130, v55, v55
	v_fmac_f32_e32 v130, v56, v56
	v_fmac_f32_e32 v130, v57, v57
	v_fmac_f32_e32 v130, v58, v58
	v_fmac_f32_e32 v130, v59, v59
	v_fmac_f32_e32 v130, v60, v60
	v_fmac_f32_e32 v130, v61, v61
	v_fmac_f32_e32 v130, v62, v62
	v_fmac_f32_e32 v130, v63, v63
	v_fmac_f32_e32 v130, v64, v64
	v_fmac_f32_e32 v130, v65, v65
	v_mul_f32_e32 v131, v66, v66
	v_fmac_f32_e32 v131, v67, v67
	v_fmac_f32_e32 v131, v68, v68
	v_fmac_f32_e32 v131, v69, v69
	v_fmac_f32_e32 v131, v70, v70
	v_fmac_f32_e32 v131, v71, v71
	v_fmac_f32_e32 v131, v72, v72
	v_fmac_f32_e32 v131, v73, v73
	v_fmac_f32_e32 v131, v74, v74
	v_fmac_f32_e32 v131, v75, v75
	v_fmac_f32_e32 v131, v76, v76
	v_fmac_f32_e32 v131, v77, v77
	v_fmac_f32_e32 v131, v78, v78
	v_fmac_f32_e32 v131, v79, v79
	v_fmac_f32_e32 v131, v80, v80
	v_fmac_f32_e32 v131, v81, v81
	v_fmac_f32_e32 v131, v82, v82
	v_fmac_f32_e32 v131, v83, v83
	v_fmac_f32_e32 v131, v84, v84
	v_fmac_f32_e32 v131, v85, v85
	v_fmac_f32_e32 v131, v86, v86
	v_fmac_f32_e32 v131, v87, v87
	v_fmac_f32_e32 v131, v88, v88
	v_fmac_f32_e32 v131, v89, v89
	v_fmac_f32_e32 v131, v90, v90
	v_fmac_f32_e32 v131, v91, v91
	v_fmac_f32_e32 v131, v92, v92
	v_fmac_f32_e32 v131, v93, v93
	v_fmac_f32_e32 v131, v94, v94
	v_fmac_f32_e32 v131, v95, v95
	v_fmac_f32_e32 v131, v96, v96
	v_fmac_f32_e32 v131, v97, v97
	v_mul_f32_e32 v132, v98, v98
	v_fmac_f32_e32 v132, v99, v99
	v_fmac_f32_e32 v132, v100, v100
	v_fmac_f32_e32 v132, v101, v101
	v_fmac_f32_e32 v132, v102, v102
	v_fmac_f32_e32 v132, v103, v103
	v_fmac_f32_e32 v132, v104, v104
	v_fmac_f32_e32 v132, v105, v105
	v_fmac_f32_e32 v132, v106, v106
	v_fmac_f32_e32 v132, v107, v107
	v_fmac_f32_e32 v132, v108, v108
	v_fmac_f32_e32 v132, v109, v109
	v_fmac_f32_e32 v132, v110, v110
	v_fmac_f32_e32 v132, v111, v111
	v_fmac_f32_e32 v132, v112, v112
	v_fmac_f32_e32 v132, v113, v113
	v_fmac_f32_e32 v132, v114, v114
	v_fmac_f32_e32 v132, v115, v115
	v_fmac_f32_e32 v132, v116, v116
	v_fmac_f32_e32 v132, v117, v117
	v_fmac_f32_e32 v132, v118, v118
	v_fmac_f32_e32 v132, v119, v119
	v_fmac_f32_e32 v132, v120, v120
	v_fmac_f32_e32 v132, v121, v121
	v_fmac_f32_e32 v132, v122, v122
	v_fmac_f32_e32 v132, v123, v123
	v_fmac_f32_e32 v132, v124, v124
	v_fmac_f32_e32 v132, v125, v125
	v_fmac_f32_e32 v132, v126, v126
	v_fmac_f32_e32 v132, v127, v127
	v_fmac_f32_e32 v132, v128, v128
	v_fmac_f32_e32 v132, v129, v129
	v_xor_b32_e32 v136, 4, v20
	ds_bpermute_b32 v133, v136, v130
	ds_bpermute_b32 v134, v136, v131
	ds_bpermute_b32 v135, v136, v132
	s_waitcnt lgkmcnt(0)
	v_add_f32_e32 v130, v130, v133
	v_add_f32_e32 v131, v131, v134
	v_add_f32_e32 v132, v132, v135
	v_xor_b32_e32 v136, 8, v20
	ds_bpermute_b32 v133, v136, v130
	ds_bpermute_b32 v134, v136, v131
	ds_bpermute_b32 v135, v136, v132
	s_waitcnt lgkmcnt(0)
	v_add_f32_e32 v130, v130, v133
	v_add_f32_e32 v131, v131, v134
	v_add_f32_e32 v132, v132, v135
	v_xor_b32_e32 v136, 16, v20
	ds_bpermute_b32 v133, v136, v130
	ds_bpermute_b32 v134, v136, v131
	ds_bpermute_b32 v135, v136, v132
	s_waitcnt lgkmcnt(0)
	v_add_f32_e32 v130, v130, v133
	v_add_f32_e32 v131, v131, v134
	v_add_f32_e32 v132, v132, v135
	v_xor_b32_e32 v136, 32, v20
	ds_bpermute_b32 v133, v136, v130
	ds_bpermute_b32 v134, v136, v131
	ds_bpermute_b32 v135, v136, v132
	s_waitcnt lgkmcnt(0)
	v_add_f32_e32 v130, v130, v133
	v_add_f32_e32 v131, v131, v134
	v_add_f32_e32 v132, v132, v135
	v_xor_b32_e32 v136, 64, v20
	ds_bpermute_b32 v133, v136, v130
	ds_bpermute_b32 v134, v136, v131
	ds_bpermute_b32 v135, v136, v132
	s_waitcnt lgkmcnt(0)
	v_add_f32_e32 v130, v130, v133
	v_add_f32_e32 v131, v131, v134
	v_add_f32_e32 v132, v132, v135
	v_xor_b32_e32 v136, 128, v20
	ds_bpermute_b32 v133, v136, v130
	ds_bpermute_b32 v134, v136, v131
	ds_bpermute_b32 v135, v136, v132
	s_waitcnt lgkmcnt(0)
	v_add_f32_e32 v130, v130, v133
	v_add_f32_e32 v131, v131, v134
	v_add_f32_e32 v132, v132, v135
	v_mov_b32_e32 v30, v130
	v_fmamk_f32 v30, v30, 0x3a000000, v171
	v_mul_f32_e32 v28, 0x4f800000, v30
	v_cmp_gt_f32_e32 vcc, s51, v30
	s_nop 1
	v_cndmask_b32_e32 v30, v30, v28, vcc
	v_sqrt_f32_e32 v28, v30
	s_nop 0
	v_add_u32_e32 v29, -1, v28
	v_add_u32_e32 v31, 1, v28
	v_fma_f32 v32, -v29, v28, v30
	v_fma_f32 v33, -v31, v28, v30
	v_cmp_ge_f32_e64 s[34:35], 0, v32
	s_nop 1
	v_cndmask_b32_e64 v28, v28, v29, s[34:35]
	v_cmp_lt_f32_e64 s[34:35], 0, v33
	s_nop 1
	v_cndmask_b32_e64 v28, v28, v31, s[34:35]
	v_mul_f32_e32 v29, 0x37800000, v28
	v_cndmask_b32_e32 v28, v28, v29, vcc
	v_cmp_class_f32_e32 vcc, v30, v172
	s_nop 1
	v_cndmask_b32_e32 v30, v28, v30, vcc
	v_div_scale_f32 v28, s[34:35], v30, v30, 1.0
	v_rcp_f32_e32 v29, v28
	v_div_scale_f32 v31, vcc, 1.0, v30, 1.0
	v_fma_f32 v32, -v28, v29, 1.0
	v_fmac_f32_e32 v29, v32, v29
	v_mul_f32_e32 v32, v31, v29
	v_fma_f32 v33, -v28, v32, v31
	v_fmac_f32_e32 v32, v33, v29
	v_fma_f32 v28, -v28, v32, v31
	v_div_fmas_f32 v28, v28, v29, v32
	v_div_fixup_f32 v30, v28, v30, 1.0
	v_mov_b32_e32 v24, s24
	ds_write_b32 v24, v30
	v_mov_b32_e32 v30, v131
	v_fmamk_f32 v30, v30, 0x3a000000, v171
	v_mul_f32_e32 v28, 0x4f800000, v30
	v_cmp_gt_f32_e32 vcc, s51, v30
	s_nop 1
	v_cndmask_b32_e32 v30, v30, v28, vcc
	v_sqrt_f32_e32 v28, v30
	s_nop 0
	v_add_u32_e32 v29, -1, v28
	v_add_u32_e32 v31, 1, v28
	v_fma_f32 v32, -v29, v28, v30
	v_fma_f32 v33, -v31, v28, v30
	v_cmp_ge_f32_e64 s[34:35], 0, v32
	s_nop 1
	v_cndmask_b32_e64 v28, v28, v29, s[34:35]
	v_cmp_lt_f32_e64 s[34:35], 0, v33
	s_nop 1
	v_cndmask_b32_e64 v28, v28, v31, s[34:35]
	v_mul_f32_e32 v29, 0x37800000, v28
	v_cndmask_b32_e32 v28, v28, v29, vcc
	v_cmp_class_f32_e32 vcc, v30, v172
	s_nop 1
	v_cndmask_b32_e32 v30, v28, v30, vcc
	v_div_scale_f32 v28, s[34:35], v30, v30, 1.0
	v_rcp_f32_e32 v29, v28
	v_div_scale_f32 v31, vcc, 1.0, v30, 1.0
	v_fma_f32 v32, -v28, v29, 1.0
	v_fmac_f32_e32 v29, v32, v29
	v_mul_f32_e32 v32, v31, v29
	v_fma_f32 v33, -v28, v32, v31
	v_fmac_f32_e32 v32, v33, v29
	v_fma_f32 v28, -v28, v32, v31
	v_div_fmas_f32 v28, v28, v29, v32
	v_div_fixup_f32 v30, v28, v30, 1.0
	v_mov_b32_e32 v24, s25
	ds_write_b32 v24, v30
	v_mov_b32_e32 v30, v132
	v_fmamk_f32 v30, v30, 0x3a000000, v171
	v_mul_f32_e32 v28, 0x4f800000, v30
	v_cmp_gt_f32_e32 vcc, s51, v30
	s_nop 1
	v_cndmask_b32_e32 v30, v30, v28, vcc
	v_sqrt_f32_e32 v28, v30
	s_nop 0
	v_add_u32_e32 v29, -1, v28
	v_add_u32_e32 v31, 1, v28
	v_fma_f32 v32, -v29, v28, v30
	v_fma_f32 v33, -v31, v28, v30
	v_cmp_ge_f32_e64 s[34:35], 0, v32
	s_nop 1
	v_cndmask_b32_e64 v28, v28, v29, s[34:35]
	v_cmp_lt_f32_e64 s[34:35], 0, v33
	s_nop 1
	v_cndmask_b32_e64 v28, v28, v31, s[34:35]
	v_mul_f32_e32 v29, 0x37800000, v28
	v_cndmask_b32_e32 v28, v28, v29, vcc
	v_cmp_class_f32_e32 vcc, v30, v172
	s_nop 1
	v_cndmask_b32_e32 v30, v28, v30, vcc
	v_div_scale_f32 v28, s[34:35], v30, v30, 1.0
	v_rcp_f32_e32 v29, v28
	v_div_scale_f32 v31, vcc, 1.0, v30, 1.0
	v_fma_f32 v32, -v28, v29, 1.0
	v_fmac_f32_e32 v29, v32, v29
	v_mul_f32_e32 v32, v31, v29
	v_fma_f32 v33, -v28, v32, v31
	v_fmac_f32_e32 v32, v33, v29
	v_fma_f32 v28, -v28, v32, v31
	v_div_fmas_f32 v28, v28, v29, v32
	v_div_fixup_f32 v30, v28, v30, 1.0
	v_mov_b32_e32 v24, s26
	ds_write_b32 v24, v30
	s_add_u32 s41, s2, 24
	s_max_u32 s41, s41, s62
	s_min_u32 s41, s41, 46
	s_lshl_b32 s24, s41, 2
	s_add_i32 s41, s41, s52
	s_lshl_b32 s12, s41, 13
	s_lshr_b32 s13, s41, 19
	s_add_u32 s20, s16, s12
	s_addc_u32 s21, s17, s13
	s_add_u32 s48, s20, 0x1000
	s_addc_u32 s49, s21, 0
	global_load_dwordx4 v[34:37], v23, s[20:21] offset:0
	global_load_dwordx4 v[38:41], v23, s[20:21] offset:1024
	global_load_dwordx4 v[42:45], v23, s[20:21] offset:2048
	global_load_dwordx4 v[46:49], v23, s[20:21] offset:3072
	global_load_dwordx4 v[50:53], v23, s[48:49] offset:0
	global_load_dwordx4 v[54:57], v23, s[48:49] offset:1024
	global_load_dwordx4 v[58:61], v23, s[48:49] offset:2048
	global_load_dwordx4 v[62:65], v23, s[48:49] offset:3072
	s_add_u32 s41, s2, 32
	s_max_u32 s41, s41, s62
	s_min_u32 s41, s41, 46
	s_lshl_b32 s25, s41, 2
	s_add_i32 s41, s41, s52
	s_lshl_b32 s12, s41, 13
	s_lshr_b32 s13, s41, 19
	s_add_u32 s20, s16, s12
	s_addc_u32 s21, s17, s13
	s_add_u32 s48, s20, 0x1000
	s_addc_u32 s49, s21, 0
	global_load_dwordx4 v[66:69], v23, s[20:21] offset:0
	global_load_dwordx4 v[70:73], v23, s[20:21] offset:1024
	global_load_dwordx4 v[74:77], v23, s[20:21] offset:2048
	global_load_dwordx4 v[78:81], v23, s[20:21] offset:3072
	global_load_dwordx4 v[82:85], v23, s[48:49] offset:0
	global_load_dwordx4 v[86:89], v23, s[48:49] offset:1024
	global_load_dwordx4 v[90:93], v23, s[48:49] offset:2048
	global_load_dwordx4 v[94:97], v23, s[48:49] offset:3072
	s_add_u32 s41, s2, 40
	s_max_u32 s41, s41, s62
	s_min_u32 s41, s41, 46
	s_lshl_b32 s26, s41, 2
	s_add_i32 s41, s41, s52
	s_lshl_b32 s12, s41, 13
	s_lshr_b32 s13, s41, 19
	s_add_u32 s20, s16, s12
	s_addc_u32 s21, s17, s13
	s_add_u32 s48, s20, 0x1000
	s_addc_u32 s49, s21, 0
	global_load_dwordx4 v[98:101], v23, s[20:21] offset:0
	global_load_dwordx4 v[102:105], v23, s[20:21] offset:1024
	global_load_dwordx4 v[106:109], v23, s[20:21] offset:2048
	global_load_dwordx4 v[110:113], v23, s[20:21] offset:3072
	global_load_dwordx4 v[114:117], v23, s[48:49] offset:0
	global_load_dwordx4 v[118:121], v23, s[48:49] offset:1024
	global_load_dwordx4 v[122:125], v23, s[48:49] offset:2048
	global_load_dwordx4 v[126:129], v23, s[48:49] offset:3072
	s_waitcnt vmcnt(0)
	v_mul_f32_e32 v130, v34, v34
	v_fmac_f32_e32 v130, v35, v35
	v_fmac_f32_e32 v130, v36, v36
	v_fmac_f32_e32 v130, v37, v37
	v_fmac_f32_e32 v130, v38, v38
	v_fmac_f32_e32 v130, v39, v39
	v_fmac_f32_e32 v130, v40, v40
	v_fmac_f32_e32 v130, v41, v41
	v_fmac_f32_e32 v130, v42, v42
	v_fmac_f32_e32 v130, v43, v43
	v_fmac_f32_e32 v130, v44, v44
	v_fmac_f32_e32 v130, v45, v45
	v_fmac_f32_e32 v130, v46, v46
	v_fmac_f32_e32 v130, v47, v47
	v_fmac_f32_e32 v130, v48, v48
	v_fmac_f32_e32 v130, v49, v49
	v_fmac_f32_e32 v130, v50, v50
	v_fmac_f32_e32 v130, v51, v51
	v_fmac_f32_e32 v130, v52, v52
	v_fmac_f32_e32 v130, v53, v53
	v_fmac_f32_e32 v130, v54, v54
	v_fmac_f32_e32 v130, v55, v55
	v_fmac_f32_e32 v130, v56, v56
	v_fmac_f32_e32 v130, v57, v57
	v_fmac_f32_e32 v130, v58, v58
	v_fmac_f32_e32 v130, v59, v59
	v_fmac_f32_e32 v130, v60, v60
	v_fmac_f32_e32 v130, v61, v61
	v_fmac_f32_e32 v130, v62, v62
	v_fmac_f32_e32 v130, v63, v63
	v_fmac_f32_e32 v130, v64, v64
	v_fmac_f32_e32 v130, v65, v65
	v_mul_f32_e32 v131, v66, v66
	v_fmac_f32_e32 v131, v67, v67
	v_fmac_f32_e32 v131, v68, v68
	v_fmac_f32_e32 v131, v69, v69
	v_fmac_f32_e32 v131, v70, v70
	v_fmac_f32_e32 v131, v71, v71
	v_fmac_f32_e32 v131, v72, v72
	v_fmac_f32_e32 v131, v73, v73
	v_fmac_f32_e32 v131, v74, v74
	v_fmac_f32_e32 v131, v75, v75
	v_fmac_f32_e32 v131, v76, v76
	v_fmac_f32_e32 v131, v77, v77
	v_fmac_f32_e32 v131, v78, v78
	v_fmac_f32_e32 v131, v79, v79
	v_fmac_f32_e32 v131, v80, v80
	v_fmac_f32_e32 v131, v81, v81
	v_fmac_f32_e32 v131, v82, v82
	v_fmac_f32_e32 v131, v83, v83
	v_fmac_f32_e32 v131, v84, v84
	v_fmac_f32_e32 v131, v85, v85
	v_fmac_f32_e32 v131, v86, v86
	v_fmac_f32_e32 v131, v87, v87
	v_fmac_f32_e32 v131, v88, v88
	v_fmac_f32_e32 v131, v89, v89
	v_fmac_f32_e32 v131, v90, v90
	v_fmac_f32_e32 v131, v91, v91
	v_fmac_f32_e32 v131, v92, v92
	v_fmac_f32_e32 v131, v93, v93
	v_fmac_f32_e32 v131, v94, v94
	v_fmac_f32_e32 v131, v95, v95
	v_fmac_f32_e32 v131, v96, v96
	v_fmac_f32_e32 v131, v97, v97
	v_mul_f32_e32 v132, v98, v98
	v_fmac_f32_e32 v132, v99, v99
	v_fmac_f32_e32 v132, v100, v100
	v_fmac_f32_e32 v132, v101, v101
	v_fmac_f32_e32 v132, v102, v102
	v_fmac_f32_e32 v132, v103, v103
	v_fmac_f32_e32 v132, v104, v104
	v_fmac_f32_e32 v132, v105, v105
	v_fmac_f32_e32 v132, v106, v106
	v_fmac_f32_e32 v132, v107, v107
	v_fmac_f32_e32 v132, v108, v108
	v_fmac_f32_e32 v132, v109, v109
	v_fmac_f32_e32 v132, v110, v110
	v_fmac_f32_e32 v132, v111, v111
	v_fmac_f32_e32 v132, v112, v112
	v_fmac_f32_e32 v132, v113, v113
	v_fmac_f32_e32 v132, v114, v114
	v_fmac_f32_e32 v132, v115, v115
	v_fmac_f32_e32 v132, v116, v116
	v_fmac_f32_e32 v132, v117, v117
	v_fmac_f32_e32 v132, v118, v118
	v_fmac_f32_e32 v132, v119, v119
	v_fmac_f32_e32 v132, v120, v120
	v_fmac_f32_e32 v132, v121, v121
	v_fmac_f32_e32 v132, v122, v122
	v_fmac_f32_e32 v132, v123, v123
	v_fmac_f32_e32 v132, v124, v124
	v_fmac_f32_e32 v132, v125, v125
	v_fmac_f32_e32 v132, v126, v126
	v_fmac_f32_e32 v132, v127, v127
	v_fmac_f32_e32 v132, v128, v128
	v_fmac_f32_e32 v132, v129, v129
	v_xor_b32_e32 v136, 4, v20
	ds_bpermute_b32 v133, v136, v130
	ds_bpermute_b32 v134, v136, v131
	ds_bpermute_b32 v135, v136, v132
	s_waitcnt lgkmcnt(0)
	v_add_f32_e32 v130, v130, v133
	v_add_f32_e32 v131, v131, v134
	v_add_f32_e32 v132, v132, v135
	v_xor_b32_e32 v136, 8, v20
	ds_bpermute_b32 v133, v136, v130
	ds_bpermute_b32 v134, v136, v131
	ds_bpermute_b32 v135, v136, v132
	s_waitcnt lgkmcnt(0)
	v_add_f32_e32 v130, v130, v133
	v_add_f32_e32 v131, v131, v134
	v_add_f32_e32 v132, v132, v135
	v_xor_b32_e32 v136, 16, v20
	ds_bpermute_b32 v133, v136, v130
	ds_bpermute_b32 v134, v136, v131
	ds_bpermute_b32 v135, v136, v132
	s_waitcnt lgkmcnt(0)
	v_add_f32_e32 v130, v130, v133
	v_add_f32_e32 v131, v131, v134
	v_add_f32_e32 v132, v132, v135
	v_xor_b32_e32 v136, 32, v20
	ds_bpermute_b32 v133, v136, v130
	ds_bpermute_b32 v134, v136, v131
	ds_bpermute_b32 v135, v136, v132
	s_waitcnt lgkmcnt(0)
	v_add_f32_e32 v130, v130, v133
	v_add_f32_e32 v131, v131, v134
	v_add_f32_e32 v132, v132, v135
	v_xor_b32_e32 v136, 64, v20
	ds_bpermute_b32 v133, v136, v130
	ds_bpermute_b32 v134, v136, v131
	ds_bpermute_b32 v135, v136, v132
	s_waitcnt lgkmcnt(0)
	v_add_f32_e32 v130, v130, v133
	v_add_f32_e32 v131, v131, v134
	v_add_f32_e32 v132, v132, v135
	v_xor_b32_e32 v136, 128, v20
	ds_bpermute_b32 v133, v136, v130
	ds_bpermute_b32 v134, v136, v131
	ds_bpermute_b32 v135, v136, v132
	s_waitcnt lgkmcnt(0)
	v_add_f32_e32 v130, v130, v133
	v_add_f32_e32 v131, v131, v134
	v_add_f32_e32 v132, v132, v135
	v_mov_b32_e32 v30, v130
	v_fmamk_f32 v30, v30, 0x3a000000, v171
	v_mul_f32_e32 v28, 0x4f800000, v30
	v_cmp_gt_f32_e32 vcc, s51, v30
	s_nop 1
	v_cndmask_b32_e32 v30, v30, v28, vcc
	v_sqrt_f32_e32 v28, v30
	s_nop 0
	v_add_u32_e32 v29, -1, v28
	v_add_u32_e32 v31, 1, v28
	v_fma_f32 v32, -v29, v28, v30
	v_fma_f32 v33, -v31, v28, v30
	v_cmp_ge_f32_e64 s[34:35], 0, v32
	s_nop 1
	v_cndmask_b32_e64 v28, v28, v29, s[34:35]
	v_cmp_lt_f32_e64 s[34:35], 0, v33
	s_nop 1
	v_cndmask_b32_e64 v28, v28, v31, s[34:35]
	v_mul_f32_e32 v29, 0x37800000, v28
	v_cndmask_b32_e32 v28, v28, v29, vcc
	v_cmp_class_f32_e32 vcc, v30, v172
	s_nop 1
	v_cndmask_b32_e32 v30, v28, v30, vcc
	v_div_scale_f32 v28, s[34:35], v30, v30, 1.0
	v_rcp_f32_e32 v29, v28
	v_div_scale_f32 v31, vcc, 1.0, v30, 1.0
	v_fma_f32 v32, -v28, v29, 1.0
	v_fmac_f32_e32 v29, v32, v29
	v_mul_f32_e32 v32, v31, v29
	v_fma_f32 v33, -v28, v32, v31
	v_fmac_f32_e32 v32, v33, v29
	v_fma_f32 v28, -v28, v32, v31
	v_div_fmas_f32 v28, v28, v29, v32
	v_div_fixup_f32 v30, v28, v30, 1.0
	v_mov_b32_e32 v24, s24
	ds_write_b32 v24, v30
	v_mov_b32_e32 v30, v131
	v_fmamk_f32 v30, v30, 0x3a000000, v171
	v_mul_f32_e32 v28, 0x4f800000, v30
	v_cmp_gt_f32_e32 vcc, s51, v30
	s_nop 1
	v_cndmask_b32_e32 v30, v30, v28, vcc
	v_sqrt_f32_e32 v28, v30
	s_nop 0
	v_add_u32_e32 v29, -1, v28
	v_add_u32_e32 v31, 1, v28
	v_fma_f32 v32, -v29, v28, v30
	v_fma_f32 v33, -v31, v28, v30
	v_cmp_ge_f32_e64 s[34:35], 0, v32
	s_nop 1
	v_cndmask_b32_e64 v28, v28, v29, s[34:35]
	v_cmp_lt_f32_e64 s[34:35], 0, v33
	s_nop 1
	v_cndmask_b32_e64 v28, v28, v31, s[34:35]
	v_mul_f32_e32 v29, 0x37800000, v28
	v_cndmask_b32_e32 v28, v28, v29, vcc
	v_cmp_class_f32_e32 vcc, v30, v172
	s_nop 1
	v_cndmask_b32_e32 v30, v28, v30, vcc
	v_div_scale_f32 v28, s[34:35], v30, v30, 1.0
	v_rcp_f32_e32 v29, v28
	v_div_scale_f32 v31, vcc, 1.0, v30, 1.0
	v_fma_f32 v32, -v28, v29, 1.0
	v_fmac_f32_e32 v29, v32, v29
	v_mul_f32_e32 v32, v31, v29
	v_fma_f32 v33, -v28, v32, v31
	v_fmac_f32_e32 v32, v33, v29
	v_fma_f32 v28, -v28, v32, v31
	v_div_fmas_f32 v28, v28, v29, v32
	v_div_fixup_f32 v30, v28, v30, 1.0
	v_mov_b32_e32 v24, s25
	ds_write_b32 v24, v30
	v_mov_b32_e32 v30, v132
	v_fmamk_f32 v30, v30, 0x3a000000, v171
	v_mul_f32_e32 v28, 0x4f800000, v30
	v_cmp_gt_f32_e32 vcc, s51, v30
	s_nop 1
	v_cndmask_b32_e32 v30, v30, v28, vcc
	v_sqrt_f32_e32 v28, v30
	s_nop 0
	v_add_u32_e32 v29, -1, v28
	v_add_u32_e32 v31, 1, v28
	v_fma_f32 v32, -v29, v28, v30
	v_fma_f32 v33, -v31, v28, v30
	v_cmp_ge_f32_e64 s[34:35], 0, v32
	s_nop 1
	v_cndmask_b32_e64 v28, v28, v29, s[34:35]
	v_cmp_lt_f32_e64 s[34:35], 0, v33
	s_nop 1
	v_cndmask_b32_e64 v28, v28, v31, s[34:35]
	v_mul_f32_e32 v29, 0x37800000, v28
	v_cndmask_b32_e32 v28, v28, v29, vcc
	v_cmp_class_f32_e32 vcc, v30, v172
	s_nop 1
	v_cndmask_b32_e32 v30, v28, v30, vcc
	v_div_scale_f32 v28, s[34:35], v30, v30, 1.0
	v_rcp_f32_e32 v29, v28
	v_div_scale_f32 v31, vcc, 1.0, v30, 1.0
	v_fma_f32 v32, -v28, v29, 1.0
	v_fmac_f32_e32 v29, v32, v29
	v_mul_f32_e32 v32, v31, v29
	v_fma_f32 v33, -v28, v32, v31
	v_fmac_f32_e32 v32, v33, v29
	v_fma_f32 v28, -v28, v32, v31
	v_div_fmas_f32 v28, v28, v29, v32
	v_div_fixup_f32 v30, v28, v30, 1.0
	v_mov_b32_e32 v24, s26
	ds_write_b32 v24, v30
	s_waitcnt lgkmcnt(0)
	s_barrier
	s_lshl_b32 s12, s52, 13
	s_ashr_i32 s13, s52, 19
	s_add_u32 s48, s16, s12
	s_addc_u32 s49, s17, s13
	s_add_u32 s24, s48, 0x1e000
	s_addc_u32 s25, s49, 0
	s_lshl_b32 s12, s53, 13
	s_add_u32 s26, s48, s12
	s_addc_u32 s27, s49, 0
	s_mul_i32 s12, s50, 0x480
	s_add_u32 s28, s18, s12
	s_addc_u32 s29, s19, 0
	s_mul_i32 s12, s44, 0x1e000
	s_add_u32 s12, s12, 0x4200000
	s_add_u32 s30, s8, s12
	s_addc_u32 s31, s9, 0
	v_mov_b32_e32 v25, 0
	s_lshl_b32 s12, s53, 2
	v_mov_b32_e32 v26, s12
	s_cmp_eq_u32 s38, 1
	s_cbranch_scc1 .Lq0_noI
	global_load_dwordx4 v[34:37], v21, s[48:49]
	s_add_u32 s48, s48, 0x2000
	s_addc_u32 s49, s49, 0
	global_load_dwordx4 v[38:41], v21, s[48:49]
	s_add_u32 s48, s48, 0x2000
	s_addc_u32 s49, s49, 0
	global_load_dwordx4 v[42:45], v21, s[48:49]
	s_add_u32 s48, s48, 0x2000
	s_addc_u32 s49, s49, 0
	global_load_dwordx4 v[46:49], v21, s[48:49]
	s_add_u32 s48, s48, 0x2000
	s_addc_u32 s49, s49, 0
	global_load_dwordx4 v[50:53], v21, s[48:49]
	s_add_u32 s48, s48, 0x2000
	s_addc_u32 s49, s49, 0
	global_load_dwordx4 v[54:57], v21, s[48:49]
	s_add_u32 s48, s48, 0x2000
	s_addc_u32 s49, s49, 0
	global_load_dwordx4 v[58:61], v21, s[48:49]
	s_add_u32 s48, s48, 0x2000
	s_addc_u32 s49, s49, 0
	global_load_dwordx4 v[62:65], v21, s[48:49]
	s_add_u32 s48, s48, 0x2000
	s_addc_u32 s49, s49, 0
	global_load_dwordx4 v[66:69], v21, s[48:49]
	s_add_u32 s48, s48, 0x2000
	s_addc_u32 s49, s49, 0
	global_load_dwordx4 v[70:73], v21, s[48:49]
	s_add_u32 s48, s48, 0x2000
	s_addc_u32 s49, s49, 0
	global_load_dwordx4 v[74:77], v21, s[48:49]
	s_add_u32 s48, s48, 0x2000
	s_addc_u32 s49, s49, 0
	global_load_dwordx4 v[78:81], v21, s[48:49]
	s_add_u32 s48, s48, 0x2000
	s_addc_u32 s49, s49, 0
	global_load_dwordx4 v[82:85], v21, s[48:49]
	s_add_u32 s48, s48, 0x2000
	s_addc_u32 s49, s49, 0
	global_load_dwordx4 v[86:89], v21, s[48:49]
	s_add_u32 s48, s48, 0x2000
	s_addc_u32 s49, s49, 0
	global_load_dwordx4 v[90:93], v21, s[48:49]
	s_add_u32 s48, s48, 0x2000
	s_addc_u32 s49, s49, 0
